# P1 epilogue: the two drain waits behind the conv loads become counted vmcnt(6) (the 6 younger boundary stores no longer gate the loads)
# baseline (speedup 1.0000x reference)
.LBB0_126:
	s_or_b64 exec, exec, s[52:53]
	v_mov_b32_dpp v214, v80 row_ror:1 row_mask:0xf bank_mask:0xf bound_ctrl:1
	v_mov_b32_dpp v215, v81 row_ror:1 row_mask:0xf bank_mask:0xf bound_ctrl:1
	v_mov_b32_dpp v216, v82 row_ror:1 row_mask:0xf bank_mask:0xf bound_ctrl:1
	v_mov_b32_dpp v217, v83 row_ror:1 row_mask:0xf bank_mask:0xf bound_ctrl:1
	v_mov_b32_dpp v204, v124 row_ror:15 row_mask:0xf bank_mask:0xf bound_ctrl:1
	v_mov_b32_dpp v205, v125 row_ror:15 row_mask:0xf bank_mask:0xf bound_ctrl:1
	v_mov_b32_dpp v212, v126 row_ror:15 row_mask:0xf bank_mask:0xf bound_ctrl:1
	v_mov_b32_dpp v213, v127 row_ror:15 row_mask:0xf bank_mask:0xf bound_ctrl:1
	v_mov_b32_dpp v200, v112 row_ror:15 row_mask:0xf bank_mask:0xf bound_ctrl:1
	v_mov_b32_dpp v201, v113 row_ror:15 row_mask:0xf bank_mask:0xf bound_ctrl:1
	v_mov_b32_dpp v208, v114 row_ror:15 row_mask:0xf bank_mask:0xf bound_ctrl:1
	v_mov_b32_dpp v209, v115 row_ror:15 row_mask:0xf bank_mask:0xf bound_ctrl:1
	v_mov_b32_dpp v190, v72 row_ror:1 row_mask:0xf bank_mask:0xf bound_ctrl:1
	v_mov_b32_dpp v191, v73 row_ror:1 row_mask:0xf bank_mask:0xf bound_ctrl:1
	v_mov_b32_dpp v198, v74 row_ror:1 row_mask:0xf bank_mask:0xf bound_ctrl:1
	v_mov_b32_dpp v199, v75 row_ror:1 row_mask:0xf bank_mask:0xf bound_ctrl:1
	v_mov_b32_dpp v202, v120 row_ror:15 row_mask:0xf bank_mask:0xf bound_ctrl:1
	v_mov_b32_dpp v203, v121 row_ror:15 row_mask:0xf bank_mask:0xf bound_ctrl:1
	v_mov_b32_dpp v210, v122 row_ror:15 row_mask:0xf bank_mask:0xf bound_ctrl:1
	v_mov_b32_dpp v211, v123 row_ror:15 row_mask:0xf bank_mask:0xf bound_ctrl:1
	v_mov_b32_dpp v192, v104 row_ror:15 row_mask:0xf bank_mask:0xf bound_ctrl:1
	v_mov_b32_dpp v193, v105 row_ror:15 row_mask:0xf bank_mask:0xf bound_ctrl:1
	v_mov_b32_dpp v206, v106 row_ror:15 row_mask:0xf bank_mask:0xf bound_ctrl:1
	v_mov_b32_dpp v207, v107 row_ror:15 row_mask:0xf bank_mask:0xf bound_ctrl:1
	s_and_saveexec_b64 s[52:53], s[2:3]
	s_cbranch_execz .LBB0_128
	s_waitcnt vmcnt(6)
	v_pk_fma_f32 v[216:217], v[138:139], v[216:217], v[166:167]
	v_pk_fma_f32 v[214:215], v[136:137], v[214:215], v[164:165]
	v_pk_fma_f32 v[190:191], v[128:129], v[190:191], v[160:161]
	v_pk_fma_f32 v[216:217], v[126:127], v[146:147], v[216:217]
	v_pk_fma_f32 v[214:215], v[124:125], v[144:145], v[214:215]
	v_pk_fma_f32 v[190:191], v[120:121], v[132:133], v[190:191]
	v_pk_fma_f32 v[216:217], v[114:115], v[154:155], v[216:217]
	v_pk_fma_f32 v[214:215], v[112:113], v[152:153], v[214:215]
	v_pk_fma_f32 v[190:191], v[104:105], v[140:141], v[190:191]
	v_pk_fma_f32 v[216:217], v[98:99], v[158:159], v[216:217]
	v_pk_fma_f32 v[214:215], v[96:97], v[156:157], v[214:215]
	v_pk_fma_f32 v[190:191], v[88:89], v[148:149], v[190:191]
	v_ashrrev_i32_e32 v187, 31, v186
	v_pk_fma_f32 v[198:199], v[130:131], v[198:199], v[162:163]
	v_cvt_pk_bf16_f32 v214, v214, v215
	v_cvt_pk_bf16_f32 v215, v216, v217
	v_cvt_pk_bf16_f32 v216, v190, v191
	v_lshlrev_b64 v[190:191], 13, v[186:187]
	v_pk_fma_f32 v[198:199], v[122:123], v[134:135], v[198:199]
	v_lshl_add_u64 v[190:191], s[24:25], 0, v[190:191]
	v_pk_fma_f32 v[198:199], v[106:107], v[142:143], v[198:199]
	v_lshl_add_u64 v[190:191], v[188:189], 1, v[190:191]
	v_pk_fma_f32 v[198:199], v[90:91], v[150:151], v[198:199]
	s_nop 0
	v_cvt_pk_bf16_f32 v217, v198, v199
	global_store_dwordx4 v[190:191], v[214:217], off
.LBB0_128:
	s_or_b64 exec, exec, s[52:53]
	s_waitcnt vmcnt(6)
	v_pk_fma_f32 v[190:191], v[126:127], v[138:139], v[166:167]
	v_pk_fma_f32 v[198:199], v[124:125], v[136:137], v[164:165]
	v_pk_fma_f32 v[190:191], v[114:115], v[146:147], v[190:191]
	v_pk_fma_f32 v[214:215], v[122:123], v[130:131], v[162:163]
	v_pk_fma_f32 v[198:199], v[112:113], v[144:145], v[198:199]
	v_pk_fma_f32 v[190:191], v[98:99], v[154:155], v[190:191]
	v_pk_fma_f32 v[214:215], v[106:107], v[134:135], v[214:215]
	v_pk_fma_f32 v[198:199], v[96:97], v[152:153], v[198:199]
	v_pk_fma_f32 v[190:191], v[82:83], v[158:159], v[190:191]
	v_pk_fma_f32 v[214:215], v[90:91], v[142:143], v[214:215]
	v_pk_fma_f32 v[198:199], v[80:81], v[156:157], v[198:199]
	v_pk_fma_f32 v[218:219], v[74:75], v[150:151], v[214:215]
	v_cvt_pk_bf16_f32 v214, v198, v199
	v_cvt_pk_bf16_f32 v215, v190, v191
	v_or_b32_e32 v190, 1, v186
	v_pk_fma_f32 v[216:217], v[120:121], v[128:129], v[160:161]
	v_ashrrev_i32_e32 v191, 31, v190
	v_pk_fma_f32 v[216:217], v[104:105], v[132:133], v[216:217]
	v_lshlrev_b64 v[190:191], 13, v[190:191]
	v_pk_fma_f32 v[216:217], v[88:89], v[140:141], v[216:217]
	v_lshl_add_u64 v[190:191], s[24:25], 0, v[190:191]
	v_pk_fma_f32 v[216:217], v[72:73], v[148:149], v[216:217]
	v_lshl_add_u64 v[198:199], v[188:189], 1, v[190:191]
	v_lshlrev_b64 v[190:191], 1, v[188:189]
	v_cvt_pk_bf16_f32 v216, v216, v217
	v_cvt_pk_bf16_f32 v217, v218, v219
	global_store_dwordx4 v[198:199], v[214:217], off
	s_and_saveexec_b64 s[52:53], s[6:7]
	s_cbranch_execz .LBB0_130
	v_pk_fma_f32 v[214:215], v[114:115], v[138:139], v[166:167]
	v_pk_fma_f32 v[216:217], v[112:113], v[136:137], v[164:165]
	v_pk_fma_f32 v[214:215], v[98:99], v[146:147], v[214:215]
	v_pk_fma_f32 v[216:217], v[96:97], v[144:145], v[216:217]
	v_pk_fma_f32 v[214:215], v[82:83], v[154:155], v[214:215]
	v_pk_fma_f32 v[216:217], v[80:81], v[152:153], v[216:217]
	v_pk_fma_f32 v[218:219], v[158:159], v[212:213], v[214:215]
	v_pk_fma_f32 v[214:215], v[156:157], v[204:205], v[216:217]
	v_pk_fma_f32 v[216:217], v[106:107], v[130:131], v[162:163]
	v_cvt_pk_bf16_f32 v214, v214, v215
	v_cvt_pk_bf16_f32 v215, v218, v219
	v_or_b32_e32 v218, 2, v186
	v_pk_fma_f32 v[220:221], v[104:105], v[128:129], v[160:161]
	v_ashrrev_i32_e32 v219, 31, v218
	v_pk_fma_f32 v[216:217], v[90:91], v[134:135], v[216:217]
	v_pk_fma_f32 v[220:221], v[88:89], v[132:133], v[220:221]
	v_lshlrev_b64 v[218:219], 13, v[218:219]
	v_pk_fma_f32 v[216:217], v[74:75], v[142:143], v[216:217]
	v_pk_fma_f32 v[220:221], v[72:73], v[140:141], v[220:221]
	v_lshl_add_u64 v[218:219], s[24:25], 0, v[218:219]
	v_pk_fma_f32 v[222:223], v[150:151], v[210:211], v[216:217]
	v_pk_fma_f32 v[216:217], v[148:149], v[202:203], v[220:221]
	v_lshl_add_u64 v[218:219], v[218:219], 0, v[190:191]
	v_cvt_pk_bf16_f32 v216, v216, v217
	v_cvt_pk_bf16_f32 v217, v222, v223
	global_store_dwordx4 v[218:219], v[214:217], off
	s_nop 1
	v_pk_fma_f32 v[214:215], v[98:99], v[138:139], v[166:167]
	v_pk_fma_f32 v[216:217], v[96:97], v[136:137], v[164:165]
	v_pk_fma_f32 v[214:215], v[82:83], v[146:147], v[214:215]
	v_pk_fma_f32 v[216:217], v[80:81], v[144:145], v[216:217]
	v_pk_fma_f32 v[212:213], v[154:155], v[212:213], v[214:215]
	v_pk_fma_f32 v[204:205], v[152:153], v[204:205], v[216:217]
	v_pk_fma_f32 v[208:209], v[158:159], v[208:209], v[212:213]
	v_pk_fma_f32 v[212:213], v[88:89], v[128:129], v[160:161]
	v_pk_fma_f32 v[200:201], v[156:157], v[200:201], v[204:205]
	v_pk_fma_f32 v[212:213], v[72:73], v[132:133], v[212:213]
	v_cvt_pk_bf16_f32 v200, v200, v201
	v_cvt_pk_bf16_f32 v201, v208, v209
	v_pk_fma_f32 v[204:205], v[90:91], v[130:131], v[162:163]
	v_pk_fma_f32 v[202:203], v[140:141], v[202:203], v[212:213]
	v_pk_fma_f32 v[204:205], v[74:75], v[134:135], v[204:205]
	v_pk_fma_f32 v[192:193], v[148:149], v[192:193], v[202:203]
	v_pk_fma_f32 v[204:205], v[142:143], v[210:211], v[204:205]
	v_cvt_pk_bf16_f32 v202, v192, v193
	v_or_b32_e32 v192, 3, v186
	v_ashrrev_i32_e32 v193, 31, v192
	v_lshlrev_b64 v[192:193], 13, v[192:193]
	v_lshl_add_u64 v[192:193], s[24:25], 0, v[192:193]
	v_lshl_add_u64 v[192:193], v[192:193], 0, v[190:191]
	v_pk_fma_f32 v[204:205], v[150:151], v[206:207], v[204:205]
	s_nop 0
	v_cvt_pk_bf16_f32 v203, v204, v205
	global_store_dwordx4 v[192:193], v[200:203], off

.LBB0_142:
	s_or_b64 exec, exec, s[52:53]
	v_mov_b32_dpp v218, v68 row_ror:1 row_mask:0xf bank_mask:0xf bound_ctrl:1
	v_mov_b32_dpp v219, v69 row_ror:1 row_mask:0xf bank_mask:0xf bound_ctrl:1
	v_mov_b32_dpp v220, v70 row_ror:1 row_mask:0xf bank_mask:0xf bound_ctrl:1
	v_mov_b32_dpp v221, v71 row_ror:1 row_mask:0xf bank_mask:0xf bound_ctrl:1
	v_mov_b32_dpp v204, v116 row_ror:15 row_mask:0xf bank_mask:0xf bound_ctrl:1
	v_mov_b32_dpp v205, v117 row_ror:15 row_mask:0xf bank_mask:0xf bound_ctrl:1
	v_mov_b32_dpp v212, v118 row_ror:15 row_mask:0xf bank_mask:0xf bound_ctrl:1
	v_mov_b32_dpp v213, v119 row_ror:15 row_mask:0xf bank_mask:0xf bound_ctrl:1
	v_mov_b32_dpp v196, v100 row_ror:15 row_mask:0xf bank_mask:0xf bound_ctrl:1
	v_mov_b32_dpp v197, v101 row_ror:15 row_mask:0xf bank_mask:0xf bound_ctrl:1
	v_mov_b32_dpp v208, v102 row_ror:15 row_mask:0xf bank_mask:0xf bound_ctrl:1
	v_mov_b32_dpp v209, v103 row_ror:15 row_mask:0xf bank_mask:0xf bound_ctrl:1
	v_mov_b32_dpp v214, v64 row_ror:1 row_mask:0xf bank_mask:0xf bound_ctrl:1
	v_mov_b32_dpp v215, v65 row_ror:1 row_mask:0xf bank_mask:0xf bound_ctrl:1
	v_mov_b32_dpp v216, v66 row_ror:1 row_mask:0xf bank_mask:0xf bound_ctrl:1
	v_mov_b32_dpp v217, v67 row_ror:1 row_mask:0xf bank_mask:0xf bound_ctrl:1
	v_mov_b32_dpp v202, v108 row_ror:15 row_mask:0xf bank_mask:0xf bound_ctrl:1
	v_mov_b32_dpp v203, v109 row_ror:15 row_mask:0xf bank_mask:0xf bound_ctrl:1
	v_mov_b32_dpp v210, v110 row_ror:15 row_mask:0xf bank_mask:0xf bound_ctrl:1
	v_mov_b32_dpp v211, v111 row_ror:15 row_mask:0xf bank_mask:0xf bound_ctrl:1
	v_mov_b32_dpp v194, v92 row_ror:15 row_mask:0xf bank_mask:0xf bound_ctrl:1
	v_mov_b32_dpp v195, v93 row_ror:15 row_mask:0xf bank_mask:0xf bound_ctrl:1
	v_mov_b32_dpp v206, v94 row_ror:15 row_mask:0xf bank_mask:0xf bound_ctrl:1
	v_mov_b32_dpp v207, v95 row_ror:15 row_mask:0xf bank_mask:0xf bound_ctrl:1
	s_and_saveexec_b64 s[52:53], s[2:3]
	s_cbranch_execz .LBB0_144
	s_waitcnt vmcnt(6)
	v_pk_fma_f32 v[218:219], v[136:137], v[218:219], v[164:165]
	v_pk_fma_f32 v[216:217], v[130:131], v[216:217], v[158:159]
	v_pk_fma_f32 v[218:219], v[116:117], v[144:145], v[218:219]
	v_pk_fma_f32 v[214:215], v[128:129], v[214:215], v[156:157]
	v_pk_fma_f32 v[218:219], v[100:101], v[152:153], v[218:219]
	v_pk_fma_f32 v[216:217], v[110:111], v[134:135], v[216:217]
	v_pk_fma_f32 v[214:215], v[108:109], v[132:133], v[214:215]
	v_pk_fma_f32 v[218:219], v[84:85], v[160:161], v[218:219]
	v_pk_fma_f32 v[216:217], v[94:95], v[142:143], v[216:217]
	v_pk_fma_f32 v[214:215], v[92:93], v[140:141], v[214:215]
	v_pk_fma_f32 v[220:221], v[138:139], v[220:221], v[166:167]
	v_pk_fma_f32 v[222:223], v[78:79], v[150:151], v[216:217]
	v_pk_fma_f32 v[216:217], v[76:77], v[148:149], v[214:215]
	v_cvt_pk_bf16_f32 v214, v218, v219
	v_lshlrev_b64 v[218:219], 13, v[186:187]
	v_pk_fma_f32 v[220:221], v[118:119], v[146:147], v[220:221]
	v_lshl_add_u64 v[218:219], s[24:25], 0, v[218:219]
	v_pk_fma_f32 v[220:221], v[102:103], v[154:155], v[220:221]
	v_lshl_add_u64 v[218:219], v[188:189], 1, v[218:219]
	v_pk_fma_f32 v[220:221], v[86:87], v[162:163], v[220:221]
	s_nop 0
	v_cvt_pk_bf16_f32 v215, v220, v221
	v_cvt_pk_bf16_f32 v216, v216, v217
	v_cvt_pk_bf16_f32 v217, v222, v223
	global_store_dwordx4 v[218:219], v[214:217], off offset:256
.LBB0_144:
	s_or_b64 exec, exec, s[52:53]
	s_waitcnt vmcnt(6)
	v_pk_fma_f32 v[214:215], v[118:119], v[138:139], v[166:167]
	v_pk_fma_f32 v[216:217], v[116:117], v[136:137], v[164:165]
	v_pk_fma_f32 v[214:215], v[102:103], v[146:147], v[214:215]
	v_pk_fma_f32 v[216:217], v[100:101], v[144:145], v[216:217]
	v_pk_fma_f32 v[214:215], v[86:87], v[154:155], v[214:215]
	v_pk_fma_f32 v[216:217], v[84:85], v[152:153], v[216:217]
	v_pk_fma_f32 v[218:219], v[70:71], v[162:163], v[214:215]
	v_pk_fma_f32 v[214:215], v[68:69], v[160:161], v[216:217]
	v_pk_fma_f32 v[216:217], v[110:111], v[130:131], v[158:159]
	v_pk_fma_f32 v[220:221], v[108:109], v[128:129], v[156:157]
	v_pk_fma_f32 v[216:217], v[94:95], v[134:135], v[216:217]
	v_pk_fma_f32 v[220:221], v[92:93], v[132:133], v[220:221]
	v_pk_fma_f32 v[216:217], v[78:79], v[142:143], v[216:217]
	v_pk_fma_f32 v[220:221], v[76:77], v[140:141], v[220:221]
	v_pk_fma_f32 v[222:223], v[66:67], v[150:151], v[216:217]
	v_pk_fma_f32 v[216:217], v[64:65], v[148:149], v[220:221]
	v_cvt_pk_bf16_f32 v214, v214, v215
	v_cvt_pk_bf16_f32 v215, v218, v219
	s_nop 0
	v_cvt_pk_bf16_f32 v216, v216, v217
	v_cvt_pk_bf16_f32 v217, v222, v223
	global_store_dwordx4 v[198:199], v[214:217], off offset:256
	s_and_saveexec_b64 s[52:53], s[6:7]
	s_cbranch_execnz .LBB0_168
	s_or_b64 exec, exec, s[52:53]
	s_and_saveexec_b64 s[52:53], s[0:1]
	s_cbranch_execnz .LBB0_169
